# swiglu GEMM epilogues (P1,P10): row-per-lane dwordx4 stores permuted via ds_bpermute so each quad of lanes writes 64 contiguous bytes; ret_seq loop no longer waits on previous chunk's state stores; tr
# speedup vs baseline: 1.0330x; 1.0081x over previous
.LBB0_131:
	v_mul_f32_e32 v155, 0xbfb8aa3b, v124
	v_exp_f32_e32 v155, v155
	v_mul_f32_e32 v158, 0xbfb8aa3b, v125
	v_exp_f32_e32 v159, v158
	v_lshl_add_u32 v154, s28, 8, v148
	v_add_f32_e32 v155, 1.0, v155
	v_rcp_f32_e32 v158, v155
	v_add_f32_e32 v155, 1.0, v159
	v_mul_f32_e32 v159, 0xbfb8aa3b, v126
	v_exp_f32_e32 v160, v159
	v_mul_f32_e32 v159, 0xbfb8aa3b, v127
	v_exp_f32_e32 v161, v159
	v_rcp_f32_e32 v159, v155
	v_add_f32_e32 v155, 1.0, v160
	v_rcp_f32_e32 v160, v155
	v_add_f32_e32 v155, 1.0, v161
	v_rcp_f32_e32 v161, v155
	v_pk_mul_f32 v[124:125], v[124:125], v[158:159]
	v_lshl_or_b32 v144, s49, 7, v150
	v_pk_mul_f32 v[120:121], v[124:125], v[120:121]
	v_pk_mul_f32 v[124:125], v[126:127], v[160:161]
	v_cvt_pk_bf16_f32 v120, v120, v121
	v_mul_f32_e32 v121, 0xbfb8aa3b, v116
	v_pk_mul_f32 v[122:123], v[124:125], v[122:123]
	v_exp_f32_e32 v124, v121
	v_mul_f32_e32 v121, 0xbfb8aa3b, v117
	v_exp_f32_e32 v125, v121
	v_cvt_pk_bf16_f32 v121, v122, v123
	v_add_f32_e32 v122, 1.0, v124
	v_mul_f32_e32 v124, 0xbfb8aa3b, v118
	v_add_f32_e32 v123, 1.0, v125
	v_mul_f32_e32 v125, 0xbfb8aa3b, v119
	v_exp_f32_e32 v124, v124
	v_exp_f32_e32 v125, v125
	v_rcp_f32_e32 v122, v122
	v_rcp_f32_e32 v123, v123
	v_add_f32_e32 v124, 1.0, v124
	v_add_f32_e32 v125, 1.0, v125
	v_rcp_f32_e32 v124, v124
	v_rcp_f32_e32 v125, v125
	v_pk_mul_f32 v[116:117], v[116:117], v[122:123]
	v_ashrrev_i32_e32 v145, 31, v144
	v_pk_mul_f32 v[112:113], v[116:117], v[112:113]
	v_mul_f32_e32 v116, 0xbfb8aa3b, v110
	v_cvt_pk_bf16_f32 v122, v112, v113
	v_pk_mul_f32 v[112:113], v[118:119], v[124:125]
	v_mul_f32_e32 v117, 0xbfb8aa3b, v111
	v_pk_mul_f32 v[112:113], v[112:113], v[114:115]
	v_mul_f32_e32 v114, 0xbfb8aa3b, v108
	v_mul_f32_e32 v115, 0xbfb8aa3b, v109
	v_exp_f32_e32 v114, v114
	v_exp_f32_e32 v115, v115
	v_exp_f32_e32 v116, v116
	v_exp_f32_e32 v117, v117
	v_add_f32_e32 v114, 1.0, v114
	v_add_f32_e32 v115, 1.0, v115
	v_rcp_f32_e32 v114, v114
	v_rcp_f32_e32 v115, v115
	v_add_f32_e32 v116, 1.0, v116
	v_add_f32_e32 v117, 1.0, v117
	v_rcp_f32_e32 v116, v116
	v_rcp_f32_e32 v117, v117
	v_pk_mul_f32 v[108:109], v[108:109], v[114:115]
	v_mov_b64_e32 v[146:147], s[14:15]
	v_pk_mul_f32 v[104:105], v[108:109], v[104:105]
	v_pk_mul_f32 v[108:109], v[110:111], v[116:117]
	v_cvt_pk_bf16_f32 v104, v104, v105
	v_mul_f32_e32 v105, 0xbfb8aa3b, v100
	v_pk_mul_f32 v[106:107], v[108:109], v[106:107]
	v_exp_f32_e32 v108, v105
	v_mul_f32_e32 v105, 0xbfb8aa3b, v101
	v_exp_f32_e32 v109, v105
	v_cvt_pk_bf16_f32 v105, v106, v107
	v_add_f32_e32 v106, 1.0, v108
	v_mul_f32_e32 v108, 0xbfb8aa3b, v102
	v_add_f32_e32 v107, 1.0, v109
	v_mul_f32_e32 v109, 0xbfb8aa3b, v103
	v_exp_f32_e32 v108, v108
	v_exp_f32_e32 v109, v109
	v_rcp_f32_e32 v106, v106
	v_rcp_f32_e32 v107, v107
	v_add_f32_e32 v108, 1.0, v108
	v_add_f32_e32 v109, 1.0, v109
	v_rcp_f32_e32 v108, v108
	v_rcp_f32_e32 v109, v109
	v_pk_mul_f32 v[100:101], v[100:101], v[106:107]
	v_cvt_pk_bf16_f32 v123, v112, v113
	v_pk_mul_f32 v[96:97], v[100:101], v[96:97]
	v_mul_f32_e32 v100, 0xbfb8aa3b, v94
	v_cvt_pk_bf16_f32 v106, v96, v97
	v_pk_mul_f32 v[96:97], v[102:103], v[108:109]
	v_mul_f32_e32 v101, 0xbfb8aa3b, v95
	v_pk_mul_f32 v[96:97], v[96:97], v[98:99]
	v_mul_f32_e32 v98, 0xbfb8aa3b, v92
	v_mul_f32_e32 v99, 0xbfb8aa3b, v93
	v_exp_f32_e32 v98, v98
	v_exp_f32_e32 v99, v99
	v_exp_f32_e32 v100, v100
	v_exp_f32_e32 v101, v101
	v_add_f32_e32 v98, 1.0, v98
	v_add_f32_e32 v99, 1.0, v99
	v_rcp_f32_e32 v98, v98
	v_rcp_f32_e32 v99, v99
	v_add_f32_e32 v100, 1.0, v100
	v_add_f32_e32 v101, 1.0, v101
	v_rcp_f32_e32 v100, v100
	v_rcp_f32_e32 v101, v101
	v_pk_mul_f32 v[92:93], v[92:93], v[98:99]
	v_or_b32_e32 v112, 16, v154
	v_pk_mul_f32 v[88:89], v[92:93], v[88:89]
	v_pk_mul_f32 v[92:93], v[94:95], v[100:101]
	v_cvt_pk_bf16_f32 v88, v88, v89
	v_mul_f32_e32 v89, 0xbfb8aa3b, v84
	v_pk_mul_f32 v[90:91], v[92:93], v[90:91]
	v_exp_f32_e32 v92, v89
	v_mul_f32_e32 v89, 0xbfb8aa3b, v85
	v_exp_f32_e32 v93, v89
	v_cvt_pk_bf16_f32 v89, v90, v91
	v_add_f32_e32 v90, 1.0, v92
	v_mul_f32_e32 v92, 0xbfb8aa3b, v86
	v_add_f32_e32 v91, 1.0, v93
	v_mul_f32_e32 v93, 0xbfb8aa3b, v87
	v_exp_f32_e32 v92, v92
	v_exp_f32_e32 v93, v93
	v_rcp_f32_e32 v90, v90
	v_rcp_f32_e32 v91, v91
	v_add_f32_e32 v92, 1.0, v92
	v_add_f32_e32 v93, 1.0, v93
	v_rcp_f32_e32 v92, v92
	v_rcp_f32_e32 v93, v93
	v_pk_mul_f32 v[84:85], v[84:85], v[90:91]
	v_cvt_pk_bf16_f32 v107, v96, v97
	v_pk_mul_f32 v[80:81], v[84:85], v[80:81]
	v_mul_f32_e32 v84, 0xbfb8aa3b, v78
	v_cvt_pk_bf16_f32 v90, v80, v81
	v_pk_mul_f32 v[80:81], v[86:87], v[92:93]
	v_mul_f32_e32 v85, 0xbfb8aa3b, v79
	v_pk_mul_f32 v[80:81], v[80:81], v[82:83]
	v_mul_f32_e32 v82, 0xbfb8aa3b, v76
	v_mul_f32_e32 v83, 0xbfb8aa3b, v77
	v_exp_f32_e32 v82, v82
	v_exp_f32_e32 v83, v83
	v_exp_f32_e32 v84, v84
	v_exp_f32_e32 v85, v85
	v_add_f32_e32 v82, 1.0, v82
	v_add_f32_e32 v83, 1.0, v83
	v_rcp_f32_e32 v82, v82
	v_rcp_f32_e32 v83, v83
	v_add_f32_e32 v84, 1.0, v84
	v_add_f32_e32 v85, 1.0, v85
	v_rcp_f32_e32 v84, v84
	v_rcp_f32_e32 v85, v85
	v_pk_mul_f32 v[76:77], v[76:77], v[82:83]
	v_or_b32_e32 v96, 32, v154
	v_pk_mul_f32 v[72:73], v[76:77], v[72:73]
	v_pk_mul_f32 v[76:77], v[78:79], v[84:85]
	v_cvt_pk_bf16_f32 v72, v72, v73
	v_mul_f32_e32 v73, 0xbfb8aa3b, v68
	v_pk_mul_f32 v[74:75], v[76:77], v[74:75]
	v_exp_f32_e32 v76, v73
	v_mul_f32_e32 v73, 0xbfb8aa3b, v69
	v_exp_f32_e32 v77, v73
	v_cvt_pk_bf16_f32 v73, v74, v75
	v_add_f32_e32 v74, 1.0, v76
	v_mul_f32_e32 v76, 0xbfb8aa3b, v70
	v_add_f32_e32 v75, 1.0, v77
	v_mul_f32_e32 v77, 0xbfb8aa3b, v71
	v_exp_f32_e32 v76, v76
	v_exp_f32_e32 v77, v77
	v_rcp_f32_e32 v74, v74
	v_rcp_f32_e32 v75, v75
	v_add_f32_e32 v76, 1.0, v76
	v_add_f32_e32 v77, 1.0, v77
	v_rcp_f32_e32 v76, v76
	v_rcp_f32_e32 v77, v77
	v_pk_mul_f32 v[68:69], v[68:69], v[74:75]
	v_cvt_pk_bf16_f32 v91, v80, v81
	v_pk_mul_f32 v[64:65], v[68:69], v[64:65]
	v_mul_f32_e32 v68, 0xbfb8aa3b, v62
	v_cvt_pk_bf16_f32 v74, v64, v65
	v_pk_mul_f32 v[64:65], v[70:71], v[76:77]
	v_mul_f32_e32 v69, 0xbfb8aa3b, v63
	v_pk_mul_f32 v[64:65], v[64:65], v[66:67]
	v_mul_f32_e32 v66, 0xbfb8aa3b, v60
	v_mul_f32_e32 v67, 0xbfb8aa3b, v61
	v_exp_f32_e32 v66, v66
	v_exp_f32_e32 v67, v67
	v_exp_f32_e32 v68, v68
	v_exp_f32_e32 v69, v69
	v_add_f32_e32 v66, 1.0, v66
	v_add_f32_e32 v67, 1.0, v67
	v_rcp_f32_e32 v66, v66
	v_rcp_f32_e32 v67, v67
	v_add_f32_e32 v68, 1.0, v68
	v_add_f32_e32 v69, 1.0, v69
	v_rcp_f32_e32 v68, v68
	v_rcp_f32_e32 v69, v69
	v_pk_mul_f32 v[60:61], v[60:61], v[66:67]
	v_or_b32_e32 v80, 48, v154
	v_pk_mul_f32 v[56:57], v[60:61], v[56:57]
	v_pk_mul_f32 v[60:61], v[62:63], v[68:69]
	v_cvt_pk_bf16_f32 v56, v56, v57
	v_mul_f32_e32 v57, 0xbfb8aa3b, v52
	v_pk_mul_f32 v[58:59], v[60:61], v[58:59]
	v_exp_f32_e32 v60, v57
	v_mul_f32_e32 v57, 0xbfb8aa3b, v53
	v_exp_f32_e32 v61, v57
	v_cvt_pk_bf16_f32 v57, v58, v59
	v_add_f32_e32 v58, 1.0, v60
	v_mul_f32_e32 v60, 0xbfb8aa3b, v54
	v_add_f32_e32 v59, 1.0, v61
	v_mul_f32_e32 v61, 0xbfb8aa3b, v55
	v_exp_f32_e32 v60, v60
	v_exp_f32_e32 v61, v61
	v_rcp_f32_e32 v58, v58
	v_rcp_f32_e32 v59, v59
	v_add_f32_e32 v60, 1.0, v60
	v_add_f32_e32 v61, 1.0, v61
	v_rcp_f32_e32 v60, v60
	v_rcp_f32_e32 v61, v61
	v_pk_mul_f32 v[52:53], v[52:53], v[58:59]
	v_cvt_pk_bf16_f32 v75, v64, v65
	v_pk_mul_f32 v[48:49], v[52:53], v[48:49]
	v_mul_f32_e32 v52, 0xbfb8aa3b, v46
	v_cvt_pk_bf16_f32 v58, v48, v49
	v_pk_mul_f32 v[48:49], v[54:55], v[60:61]
	v_mul_f32_e32 v53, 0xbfb8aa3b, v47
	v_pk_mul_f32 v[48:49], v[48:49], v[50:51]
	v_mul_f32_e32 v50, 0xbfb8aa3b, v44
	v_mul_f32_e32 v51, 0xbfb8aa3b, v45
	v_exp_f32_e32 v50, v50
	v_exp_f32_e32 v51, v51
	v_exp_f32_e32 v52, v52
	v_exp_f32_e32 v53, v53
	v_add_f32_e32 v50, 1.0, v50
	v_add_f32_e32 v51, 1.0, v51
	v_rcp_f32_e32 v50, v50
	v_rcp_f32_e32 v51, v51
	v_add_f32_e32 v52, 1.0, v52
	v_add_f32_e32 v53, 1.0, v53
	v_rcp_f32_e32 v52, v52
	v_rcp_f32_e32 v53, v53
	v_pk_mul_f32 v[44:45], v[44:45], v[50:51]
	v_add_u32_e32 v64, 0x80, v154
	v_pk_mul_f32 v[40:41], v[44:45], v[40:41]
	v_pk_mul_f32 v[44:45], v[46:47], v[52:53]
	v_cvt_pk_bf16_f32 v40, v40, v41
	v_mul_f32_e32 v41, 0xbfb8aa3b, v36
	v_pk_mul_f32 v[42:43], v[44:45], v[42:43]
	v_exp_f32_e32 v44, v41
	v_mul_f32_e32 v41, 0xbfb8aa3b, v37
	v_exp_f32_e32 v45, v41
	v_cvt_pk_bf16_f32 v41, v42, v43
	v_add_f32_e32 v42, 1.0, v44
	v_mul_f32_e32 v44, 0xbfb8aa3b, v38
	v_add_f32_e32 v43, 1.0, v45
	v_mul_f32_e32 v45, 0xbfb8aa3b, v39
	v_exp_f32_e32 v44, v44
	v_exp_f32_e32 v45, v45
	v_rcp_f32_e32 v42, v42
	v_rcp_f32_e32 v43, v43
	v_add_f32_e32 v44, 1.0, v44
	v_add_f32_e32 v45, 1.0, v45
	v_rcp_f32_e32 v44, v44
	v_rcp_f32_e32 v45, v45
	v_pk_mul_f32 v[36:37], v[36:37], v[42:43]
	v_cvt_pk_bf16_f32 v59, v48, v49
	v_pk_mul_f32 v[32:33], v[36:37], v[32:33]
	v_mul_f32_e32 v36, 0xbfb8aa3b, v30
	v_cvt_pk_bf16_f32 v42, v32, v33
	v_pk_mul_f32 v[32:33], v[38:39], v[44:45]
	v_mul_f32_e32 v37, 0xbfb8aa3b, v31
	v_pk_mul_f32 v[32:33], v[32:33], v[34:35]
	v_mul_f32_e32 v34, 0xbfb8aa3b, v28
	v_mul_f32_e32 v35, 0xbfb8aa3b, v29
	v_exp_f32_e32 v34, v34
	v_exp_f32_e32 v35, v35
	v_exp_f32_e32 v36, v36
	v_exp_f32_e32 v37, v37
	v_add_f32_e32 v34, 1.0, v34
	v_add_f32_e32 v35, 1.0, v35
	v_rcp_f32_e32 v34, v34
	v_rcp_f32_e32 v35, v35
	v_add_f32_e32 v36, 1.0, v36
	v_add_f32_e32 v37, 1.0, v37
	v_rcp_f32_e32 v36, v36
	v_rcp_f32_e32 v37, v37
	v_pk_mul_f32 v[28:29], v[28:29], v[34:35]
	v_add_u32_e32 v48, 0x90, v154
	v_pk_mul_f32 v[24:25], v[28:29], v[24:25]
	v_pk_mul_f32 v[28:29], v[30:31], v[36:37]
	v_cvt_pk_bf16_f32 v24, v24, v25
	v_mul_f32_e32 v25, 0xbfb8aa3b, v20
	v_pk_mul_f32 v[26:27], v[28:29], v[26:27]
	v_exp_f32_e32 v28, v25
	v_mul_f32_e32 v25, 0xbfb8aa3b, v21
	v_exp_f32_e32 v29, v25
	v_cvt_pk_bf16_f32 v25, v26, v27
	v_add_f32_e32 v26, 1.0, v28
	v_mul_f32_e32 v28, 0xbfb8aa3b, v22
	v_add_f32_e32 v27, 1.0, v29
	v_mul_f32_e32 v29, 0xbfb8aa3b, v23
	v_exp_f32_e32 v28, v28
	v_exp_f32_e32 v29, v29
	v_rcp_f32_e32 v26, v26
	v_rcp_f32_e32 v27, v27
	v_add_f32_e32 v28, 1.0, v28
	v_add_f32_e32 v29, 1.0, v29
	v_rcp_f32_e32 v28, v28
	v_rcp_f32_e32 v29, v29
	v_pk_mul_f32 v[20:21], v[20:21], v[26:27]
	v_cvt_pk_bf16_f32 v43, v32, v33
	v_pk_mul_f32 v[16:17], v[20:21], v[16:17]
	v_mul_f32_e32 v20, 0xbfb8aa3b, v14
	v_cvt_pk_bf16_f32 v26, v16, v17
	v_pk_mul_f32 v[16:17], v[22:23], v[28:29]
	v_mul_f32_e32 v21, 0xbfb8aa3b, v15
	v_pk_mul_f32 v[16:17], v[16:17], v[18:19]
	v_mul_f32_e32 v18, 0xbfb8aa3b, v12
	v_mul_f32_e32 v19, 0xbfb8aa3b, v13
	v_exp_f32_e32 v18, v18
	v_exp_f32_e32 v19, v19
	v_exp_f32_e32 v20, v20
	v_exp_f32_e32 v21, v21
	v_add_f32_e32 v18, 1.0, v18
	v_add_f32_e32 v19, 1.0, v19
	v_rcp_f32_e32 v18, v18
	v_rcp_f32_e32 v19, v19
	v_add_f32_e32 v20, 1.0, v20
	v_add_f32_e32 v21, 1.0, v21
	v_rcp_f32_e32 v20, v20
	v_rcp_f32_e32 v21, v21
	v_pk_mul_f32 v[12:13], v[12:13], v[18:19]
	v_add_u32_e32 v32, 0xa0, v154
	v_pk_mul_f32 v[8:9], v[12:13], v[8:9]
	v_pk_mul_f32 v[12:13], v[14:15], v[20:21]
	v_cvt_pk_bf16_f32 v8, v8, v9
	v_mul_f32_e32 v9, 0xbfb8aa3b, v4
	v_pk_mul_f32 v[10:11], v[12:13], v[10:11]
	v_exp_f32_e32 v12, v9
	v_mul_f32_e32 v9, 0xbfb8aa3b, v5
	v_exp_f32_e32 v13, v9
	v_cvt_pk_bf16_f32 v9, v10, v11
	v_add_f32_e32 v10, 1.0, v12
	v_mul_f32_e32 v12, 0xbfb8aa3b, v6
	v_add_f32_e32 v11, 1.0, v13
	v_mul_f32_e32 v13, 0xbfb8aa3b, v7
	v_exp_f32_e32 v12, v12
	v_exp_f32_e32 v13, v13
	v_rcp_f32_e32 v10, v10
	v_rcp_f32_e32 v11, v11
	v_add_f32_e32 v12, 1.0, v12
	v_add_f32_e32 v13, 1.0, v13
	v_rcp_f32_e32 v12, v12
	v_rcp_f32_e32 v13, v13
	v_pk_mul_f32 v[4:5], v[4:5], v[10:11]
	v_cvt_pk_bf16_f32 v27, v16, v17
	v_pk_mul_f32 v[0:1], v[4:5], v[0:1]
	v_add_u32_e32 v16, 0xb0, v154
	v_cvt_pk_bf16_f32 v10, v0, v1
	v_pk_mul_f32 v[0:1], v[6:7], v[12:13]
	v_mad_i64_i32 v[156:157], s[30:31], v154, s48, v[146:147]
	v_lshlrev_b64 v[144:145], 1, v[144:145]
	v_mad_i64_i32 v[112:113], s[30:31], v112, s48, v[146:147]
	v_mad_i64_i32 v[96:97], s[30:31], v96, s48, v[146:147]
	v_mad_i64_i32 v[80:81], s[30:31], v80, s48, v[146:147]
	v_mad_i64_i32 v[64:65], s[30:31], v64, s48, v[146:147]
	v_mad_i64_i32 v[48:49], s[30:31], v48, s48, v[146:147]
	v_mad_i64_i32 v[32:33], s[30:31], v32, s48, v[146:147]
	v_mad_i64_i32 v[16:17], s[30:31], v16, s48, v[146:147]
	v_pk_mul_f32 v[0:1], v[0:1], v[2:3]
	v_lshl_add_u64 v[156:157], v[156:157], 0, v[144:145]
	v_lshl_add_u64 v[112:113], v[112:113], 0, v[144:145]
	v_lshl_add_u64 v[96:97], v[96:97], 0, v[144:145]
	v_lshl_add_u64 v[80:81], v[80:81], 0, v[144:145]
	v_lshl_add_u64 v[64:65], v[64:65], 0, v[144:145]
	v_lshl_add_u64 v[48:49], v[48:49], 0, v[144:145]
	v_lshl_add_u64 v[32:33], v[32:33], 0, v[144:145]
	v_lshl_add_u64 v[16:17], v[16:17], 0, v[144:145]
	v_cvt_pk_bf16_f32 v11, v0, v1
	s_andn2_b64 vcc, exec, s[6:7]
	s_mov_b64 s[6:7], -1
	v_and_b32_e32 v226, 63, v252
	v_lshlrev_b32_e32 v227, 4, v226
	v_and_b32_e32 v227, 0x30, v227
	v_lshrrev_b32_e32 v228, 4, v226
	v_and_or_b32 v227, v226, 12, v227
	v_or_b32_e32 v227, v227, v228
	v_lshlrev_b32_e32 v226, 2, v227
	ds_bpermute_b32 v230, v226, v120
	ds_bpermute_b32 v231, v226, v121
	ds_bpermute_b32 v232, v226, v122
	ds_bpermute_b32 v233, v226, v123
	ds_bpermute_b32 v234, v226, v156
	ds_bpermute_b32 v235, v226, v157
	ds_bpermute_b32 v236, v226, v104
	ds_bpermute_b32 v237, v226, v105
	ds_bpermute_b32 v238, v226, v106
	ds_bpermute_b32 v239, v226, v107
	ds_bpermute_b32 v240, v226, v112
	ds_bpermute_b32 v241, v226, v113
	s_waitcnt lgkmcnt(6)
	global_store_dwordx4 v[234:235], v[230:233], off
	s_nop 0
	ds_bpermute_b32 v230, v226, v88
	ds_bpermute_b32 v231, v226, v89
	ds_bpermute_b32 v232, v226, v90
	ds_bpermute_b32 v233, v226, v91
	ds_bpermute_b32 v234, v226, v96
	ds_bpermute_b32 v235, v226, v97
	s_waitcnt lgkmcnt(6)
	global_store_dwordx4 v[240:241], v[236:239], off
	s_nop 0
	ds_bpermute_b32 v236, v226, v72
	ds_bpermute_b32 v237, v226, v73
	ds_bpermute_b32 v238, v226, v74
	ds_bpermute_b32 v239, v226, v75
	ds_bpermute_b32 v240, v226, v80
	ds_bpermute_b32 v241, v226, v81
	s_waitcnt lgkmcnt(6)
	global_store_dwordx4 v[234:235], v[230:233], off
	s_nop 0
	ds_bpermute_b32 v230, v226, v56
	ds_bpermute_b32 v231, v226, v57
	ds_bpermute_b32 v232, v226, v58
	ds_bpermute_b32 v233, v226, v59
	ds_bpermute_b32 v234, v226, v64
	ds_bpermute_b32 v235, v226, v65
	s_waitcnt lgkmcnt(6)
	global_store_dwordx4 v[240:241], v[236:239], off
	s_nop 0
	ds_bpermute_b32 v236, v226, v40
	ds_bpermute_b32 v237, v226, v41
	ds_bpermute_b32 v238, v226, v42
	ds_bpermute_b32 v239, v226, v43
	ds_bpermute_b32 v240, v226, v48
	ds_bpermute_b32 v241, v226, v49
	s_waitcnt lgkmcnt(6)
	global_store_dwordx4 v[234:235], v[230:233], off
	s_nop 0
	ds_bpermute_b32 v230, v226, v24
	ds_bpermute_b32 v231, v226, v25
	ds_bpermute_b32 v232, v226, v26
	ds_bpermute_b32 v233, v226, v27
	ds_bpermute_b32 v234, v226, v32
	ds_bpermute_b32 v235, v226, v33
	s_waitcnt lgkmcnt(6)
	global_store_dwordx4 v[240:241], v[236:239], off
	s_nop 0
	ds_bpermute_b32 v236, v226, v8
	ds_bpermute_b32 v237, v226, v9
	ds_bpermute_b32 v238, v226, v10
	ds_bpermute_b32 v239, v226, v11
	ds_bpermute_b32 v240, v226, v16
	ds_bpermute_b32 v241, v226, v17
	s_waitcnt lgkmcnt(6)
	global_store_dwordx4 v[234:235], v[230:233], off
	s_nop 0
	s_waitcnt lgkmcnt(0)
	global_store_dwordx4 v[240:241], v[236:239], off
	s_nop 0
	s_cbranch_vccnz .LBB0_120
	s_andn2_b64 vcc, exec, s[4:5]
	s_cbranch_vccnz .LBB0_119
	s_barrier
	s_branch .LBB0_119

.Lfa_e_now1:
	s_nop 3
	v_max3_f32 v0, v96, v97, v112
	v_max3_f32 v2, v98, v99, v113
	v_max3_f32 v0, v0, v114, v115
	v_max3_f32 v2, v2, v102, v103
	v_max3_f32 v0, v0, v100, v101
	v_max3_f32 v2, v2, v118, v119
	v_max3_f32 v0, v0, v116, v117
	v_max3_f32 v2, v2, v106, v107
	v_max3_f32 v0, v0, v104, v105
	v_max3_f32 v2, v2, v122, v123
	v_max3_f32 v0, v0, v120, v121
	v_max3_f32 v2, v2, v110, v111
	v_max3_f32 v0, v0, v108, v109
	v_max3_f32 v2, v2, v126, v127
	v_max3_f32 v0, v0, v124, v125
	v_max_f32_e32 v0, v0, v2
	v_mov_b32_e32 v2, v0
	s_nop 1
	v_permlane32_swap_b32_e32 v0, v2
	v_max_f32_e32 v0, v0, v2
	v_cmp_lt_f32_e32 vcc, s57, v0
	s_cbranch_vccz .Lfa_e_sm
	v_max_f32_e32 v0, v0, v0
	v_max_f32_e32 v2, 0, v0
	v_exp_f32_e64 v0, -v2
	v_add_f32_e32 v182, v182, v2
	v_xor_b32_e32 v16, 0x80000000, v182
	v_mov_b32_e32 v17, v16
	v_mov_b32_e32 v18, v16
	v_mov_b32_e32 v19, v16
	v_mov_b32_e32 v20, v16
	v_mov_b32_e32 v21, v16
	v_mov_b32_e32 v22, v16
	v_mov_b32_e32 v23, v16
	v_mov_b32_e32 v24, v16
	v_mov_b32_e32 v25, v16
	v_mov_b32_e32 v26, v16
	v_mov_b32_e32 v27, v16
	v_mov_b32_e32 v28, v16
	v_mov_b32_e32 v29, v16
	v_mov_b32_e32 v30, v16
	v_mov_b32_e32 v31, v16
	v_sub_f32_e32 v112, v112, v2
	v_sub_f32_e32 v113, v113, v2
	v_sub_f32_e32 v114, v114, v2
	v_sub_f32_e32 v115, v115, v2
	v_sub_f32_e32 v116, v116, v2
	v_sub_f32_e32 v117, v117, v2
	v_sub_f32_e32 v118, v118, v2
	v_sub_f32_e32 v119, v119, v2
	v_sub_f32_e32 v120, v120, v2
	v_sub_f32_e32 v121, v121, v2
	v_sub_f32_e32 v122, v122, v2
	v_sub_f32_e32 v123, v123, v2
	v_sub_f32_e32 v124, v124, v2
	v_sub_f32_e32 v125, v125, v2
	v_sub_f32_e32 v126, v126, v2
	v_sub_f32_e32 v127, v127, v2
	v_sub_f32_e32 v96, v96, v2
	v_sub_f32_e32 v97, v97, v2
	v_sub_f32_e32 v98, v98, v2
	v_sub_f32_e32 v99, v99, v2
	v_sub_f32_e32 v100, v100, v2
	v_sub_f32_e32 v101, v101, v2
	v_sub_f32_e32 v102, v102, v2
	v_sub_f32_e32 v103, v103, v2
	v_sub_f32_e32 v104, v104, v2
	v_sub_f32_e32 v105, v105, v2
	v_sub_f32_e32 v106, v106, v2
	v_sub_f32_e32 v107, v107, v2
	v_sub_f32_e32 v108, v108, v2
	v_sub_f32_e32 v109, v109, v2
	v_sub_f32_e32 v110, v110, v2
	v_sub_f32_e32 v111, v111, v2
	v_mul_f32_e32 v183, v183, v0
	v_pk_mul_f32 v[94:95], v[94:95], v[0:1] op_sel_hi:[1,0]
	v_pk_mul_f32 v[92:93], v[92:93], v[0:1] op_sel_hi:[1,0]
	v_pk_mul_f32 v[90:91], v[90:91], v[0:1] op_sel_hi:[1,0]
	v_pk_mul_f32 v[88:89], v[88:89], v[0:1] op_sel_hi:[1,0]
	v_pk_mul_f32 v[86:87], v[86:87], v[0:1] op_sel_hi:[1,0]
	v_pk_mul_f32 v[84:85], v[84:85], v[0:1] op_sel_hi:[1,0]
	v_pk_mul_f32 v[82:83], v[82:83], v[0:1] op_sel_hi:[1,0]
	v_pk_mul_f32 v[80:81], v[80:81], v[0:1] op_sel_hi:[1,0]
	v_pk_mul_f32 v[78:79], v[78:79], v[0:1] op_sel_hi:[1,0]
	v_pk_mul_f32 v[76:77], v[76:77], v[0:1] op_sel_hi:[1,0]
	v_pk_mul_f32 v[74:75], v[74:75], v[0:1] op_sel_hi:[1,0]
	v_pk_mul_f32 v[72:73], v[72:73], v[0:1] op_sel_hi:[1,0]
	v_pk_mul_f32 v[70:71], v[70:71], v[0:1] op_sel_hi:[1,0]
	v_pk_mul_f32 v[68:69], v[68:69], v[0:1] op_sel_hi:[1,0]
	v_pk_mul_f32 v[66:67], v[66:67], v[0:1] op_sel_hi:[1,0]
	v_pk_mul_f32 v[64:65], v[64:65], v[0:1] op_sel_hi:[1,0]
	v_pk_mul_f32 v[62:63], v[62:63], v[0:1] op_sel_hi:[1,0]
	v_pk_mul_f32 v[60:61], v[60:61], v[0:1] op_sel_hi:[1,0]
	v_pk_mul_f32 v[58:59], v[58:59], v[0:1] op_sel_hi:[1,0]
	v_pk_mul_f32 v[56:57], v[56:57], v[0:1] op_sel_hi:[1,0]
	v_pk_mul_f32 v[54:55], v[54:55], v[0:1] op_sel_hi:[1,0]
	v_pk_mul_f32 v[52:53], v[52:53], v[0:1] op_sel_hi:[1,0]
	v_pk_mul_f32 v[50:51], v[50:51], v[0:1] op_sel_hi:[1,0]
	v_pk_mul_f32 v[48:49], v[48:49], v[0:1] op_sel_hi:[1,0]
	v_pk_mul_f32 v[46:47], v[46:47], v[0:1] op_sel_hi:[1,0]
	v_pk_mul_f32 v[44:45], v[44:45], v[0:1] op_sel_hi:[1,0]
	v_pk_mul_f32 v[42:43], v[42:43], v[0:1] op_sel_hi:[1,0]
	v_pk_mul_f32 v[40:41], v[40:41], v[0:1] op_sel_hi:[1,0]
	v_pk_mul_f32 v[38:39], v[38:39], v[0:1] op_sel_hi:[1,0]
	v_pk_mul_f32 v[36:37], v[36:37], v[0:1] op_sel_hi:[1,0]
	v_pk_mul_f32 v[34:35], v[34:35], v[0:1] op_sel_hi:[1,0]
	v_pk_mul_f32 v[32:33], v[32:33], v[0:1] op_sel_hi:[1,0]

.Lfa_o_now1:
	s_nop 3
	v_max3_f32 v0, v96, v97, v112
	v_max3_f32 v2, v98, v99, v113
	v_max3_f32 v0, v0, v114, v115
	v_max3_f32 v2, v2, v102, v103
	v_max3_f32 v0, v0, v100, v101
	v_max3_f32 v2, v2, v118, v119
	v_max3_f32 v0, v0, v116, v117
	v_max3_f32 v2, v2, v106, v107
	v_max3_f32 v0, v0, v104, v105
	v_max3_f32 v2, v2, v122, v123
	v_max3_f32 v0, v0, v120, v121
	v_max3_f32 v2, v2, v110, v111
	v_max3_f32 v0, v0, v108, v109
	v_max3_f32 v2, v2, v126, v127
	v_max3_f32 v0, v0, v124, v125
	v_max_f32_e32 v0, v0, v2
	v_mov_b32_e32 v2, v0
	s_nop 1
	v_permlane32_swap_b32_e32 v0, v2
	v_max_f32_e32 v0, v0, v2
	v_cmp_lt_f32_e32 vcc, s57, v0
	s_cbranch_vccz .Lfa_o_sm
	v_max_f32_e32 v0, v0, v0
	v_max_f32_e32 v0, 0, v0
	v_add_f32_e32 v182, v182, v0
	v_pk_add_f32 v[96:97], v[96:97], v[0:1] op_sel_hi:[1,0] neg_lo:[0,1] neg_hi:[0,1]
	v_pk_add_f32 v[112:113], v[112:113], v[0:1] op_sel_hi:[1,0] neg_lo:[0,1] neg_hi:[0,1]
	v_pk_add_f32 v[98:99], v[98:99], v[0:1] op_sel_hi:[1,0] neg_lo:[0,1] neg_hi:[0,1]
	v_pk_add_f32 v[114:115], v[114:115], v[0:1] op_sel_hi:[1,0] neg_lo:[0,1] neg_hi:[0,1]
	v_pk_add_f32 v[100:101], v[100:101], v[0:1] op_sel_hi:[1,0] neg_lo:[0,1] neg_hi:[0,1]
	v_pk_add_f32 v[116:117], v[116:117], v[0:1] op_sel_hi:[1,0] neg_lo:[0,1] neg_hi:[0,1]
	v_pk_add_f32 v[102:103], v[102:103], v[0:1] op_sel_hi:[1,0] neg_lo:[0,1] neg_hi:[0,1]
	v_pk_add_f32 v[118:119], v[118:119], v[0:1] op_sel_hi:[1,0] neg_lo:[0,1] neg_hi:[0,1]
	v_pk_add_f32 v[104:105], v[104:105], v[0:1] op_sel_hi:[1,0] neg_lo:[0,1] neg_hi:[0,1]
	v_pk_add_f32 v[120:121], v[120:121], v[0:1] op_sel_hi:[1,0] neg_lo:[0,1] neg_hi:[0,1]
	v_pk_add_f32 v[106:107], v[106:107], v[0:1] op_sel_hi:[1,0] neg_lo:[0,1] neg_hi:[0,1]
	v_pk_add_f32 v[122:123], v[122:123], v[0:1] op_sel_hi:[1,0] neg_lo:[0,1] neg_hi:[0,1]
	v_pk_add_f32 v[108:109], v[108:109], v[0:1] op_sel_hi:[1,0] neg_lo:[0,1] neg_hi:[0,1]
	v_pk_add_f32 v[124:125], v[124:125], v[0:1] op_sel_hi:[1,0] neg_lo:[0,1] neg_hi:[0,1]
	v_pk_add_f32 v[110:111], v[110:111], v[0:1] op_sel_hi:[1,0] neg_lo:[0,1] neg_hi:[0,1]
	v_pk_add_f32 v[126:127], v[126:127], v[0:1] op_sel_hi:[1,0] neg_lo:[0,1] neg_hi:[0,1]
	v_exp_f32_e64 v0, -v0
	v_xor_b32_e32 v16, 0x80000000, v182
	v_mov_b32_e32 v17, v16
	v_mov_b32_e32 v18, v16
	v_mov_b32_e32 v19, v16
	v_mov_b32_e32 v20, v16
	v_mov_b32_e32 v21, v16
	v_mov_b32_e32 v22, v16
	v_mov_b32_e32 v23, v16
	v_mov_b32_e32 v24, v16
	v_mov_b32_e32 v25, v16
	v_mov_b32_e32 v26, v16
	v_mov_b32_e32 v27, v16
	v_mov_b32_e32 v28, v16
	v_mov_b32_e32 v29, v16
	v_mov_b32_e32 v30, v16
	v_mov_b32_e32 v31, v16
	v_mul_f32_e32 v183, v183, v0
	v_pk_mul_f32 v[94:95], v[94:95], v[0:1] op_sel_hi:[1,0]
	v_pk_mul_f32 v[92:93], v[92:93], v[0:1] op_sel_hi:[1,0]
	v_pk_mul_f32 v[90:91], v[90:91], v[0:1] op_sel_hi:[1,0]
	v_pk_mul_f32 v[88:89], v[88:89], v[0:1] op_sel_hi:[1,0]
	v_pk_mul_f32 v[86:87], v[86:87], v[0:1] op_sel_hi:[1,0]
	v_pk_mul_f32 v[84:85], v[84:85], v[0:1] op_sel_hi:[1,0]
	v_pk_mul_f32 v[82:83], v[82:83], v[0:1] op_sel_hi:[1,0]
	v_pk_mul_f32 v[80:81], v[80:81], v[0:1] op_sel_hi:[1,0]
	v_pk_mul_f32 v[78:79], v[78:79], v[0:1] op_sel_hi:[1,0]
	v_pk_mul_f32 v[76:77], v[76:77], v[0:1] op_sel_hi:[1,0]
	v_pk_mul_f32 v[74:75], v[74:75], v[0:1] op_sel_hi:[1,0]
	v_pk_mul_f32 v[72:73], v[72:73], v[0:1] op_sel_hi:[1,0]
	v_pk_mul_f32 v[70:71], v[70:71], v[0:1] op_sel_hi:[1,0]
	v_pk_mul_f32 v[68:69], v[68:69], v[0:1] op_sel_hi:[1,0]
	v_pk_mul_f32 v[66:67], v[66:67], v[0:1] op_sel_hi:[1,0]
	v_pk_mul_f32 v[64:65], v[64:65], v[0:1] op_sel_hi:[1,0]
	v_pk_mul_f32 v[62:63], v[62:63], v[0:1] op_sel_hi:[1,0]
	v_pk_mul_f32 v[60:61], v[60:61], v[0:1] op_sel_hi:[1,0]
	v_pk_mul_f32 v[58:59], v[58:59], v[0:1] op_sel_hi:[1,0]
	v_pk_mul_f32 v[56:57], v[56:57], v[0:1] op_sel_hi:[1,0]
	v_pk_mul_f32 v[54:55], v[54:55], v[0:1] op_sel_hi:[1,0]
	v_pk_mul_f32 v[52:53], v[52:53], v[0:1] op_sel_hi:[1,0]
	v_pk_mul_f32 v[50:51], v[50:51], v[0:1] op_sel_hi:[1,0]
	v_pk_mul_f32 v[48:49], v[48:49], v[0:1] op_sel_hi:[1,0]
	v_pk_mul_f32 v[46:47], v[46:47], v[0:1] op_sel_hi:[1,0]
	v_pk_mul_f32 v[44:45], v[44:45], v[0:1] op_sel_hi:[1,0]
	v_pk_mul_f32 v[42:43], v[42:43], v[0:1] op_sel_hi:[1,0]
	v_pk_mul_f32 v[40:41], v[40:41], v[0:1] op_sel_hi:[1,0]
	v_pk_mul_f32 v[38:39], v[38:39], v[0:1] op_sel_hi:[1,0]
	v_pk_mul_f32 v[36:37], v[36:37], v[0:1] op_sel_hi:[1,0]
	v_pk_mul_f32 v[34:35], v[34:35], v[0:1] op_sel_hi:[1,0]
	v_pk_mul_f32 v[32:33], v[32:33], v[0:1] op_sel_hi:[1,0]

.LBB0_748:
	s_andn2_b64 vcc, exec, s[4:5]
	s_cbranch_vccnz .LBB0_659
	v_and_b32_e32 v0, 3, v178
	v_cvt_f32_ubyte0_e32 v2, v0
	v_sub_f32_e32 v2, 0xc0a00000, v2
	v_cmp_gt_f32_e32 vcc, s51, v2
	s_and_b64 s[0:1], vcc, exec
	s_cselect_b32 s0, 0xffffffc0, 0
	v_cndmask_b32_e32 v4, 0, v187, vcc
	v_add_f32_e32 v2, v2, v4
	v_exp_f32_e32 v2, v2
	v_mov_b32_e32 v3, v252
	v_lshlrev_b32_e32 v4, 10, v178
	v_ldexp_f32 v2, v2, s0
	v_sub_f32_e32 v2, 1.0, v2
	v_log_f32_e32 v5, v2
	v_bfe_u32 v62, v3, 5, 1
	v_and_b32_e32 v6, 0xfffff000, v4
	v_ashrrev_i32_e32 v14, 4, v3
	v_mul_f32_e32 v7, 0x42800000, v5
	v_cmp_gt_f32_e32 vcc, s51, v7
	s_and_b64 s[4:5], vcc, exec
	s_cselect_b32 s0, 0xffffffc0, 0
	v_cndmask_b32_e32 v7, 0, v187, vcc
	v_fmac_f32_e32 v7, 0x42800000, v5
	v_exp_f32_e32 v7, v7
	v_readfirstlane_b32 s8, v3
	v_and_b32_e32 v63, 31, v3
	v_lshlrev_b32_e32 v8, 2, v3
	v_ldexp_f32 v50, v7, s0
	v_bfe_u32 v7, v3, 2, 2
	v_lshl_or_b32 v12, v62, 3, v7
	v_and_b32_e32 v7, 16, v3
	v_add_u32_e32 v15, v14, v6
	v_lshlrev_b32_e32 v3, 4, v3
	v_and_or_b32 v13, v8, 12, v7
	v_mov_b64_e32 v[6:7], s[18:19]
	v_and_b32_e32 v10, 0xf0, v3
	v_add_u32_e32 v3, 32, v15
	v_mad_i64_i32 v[8:9], s[4:5], v15, s52, v[6:7]
	v_lshlrev_b32_e32 v0, 8, v0
	v_mad_i64_i32 v[6:7], s[4:5], v3, s52, v[6:7]
	v_lshl_add_u64 v[8:9], v[8:9], 0, v[0:1]
	v_mov_b32_e32 v11, v1
	v_lshl_add_u64 v[6:7], v[6:7], 0, v[0:1]
	v_lshl_add_u64 v[8:9], v[8:9], 0, v[10:11]
	v_lshl_add_u64 v[6:7], v[6:7], 0, v[10:11]
	global_load_dwordx4 v[34:37], v[8:9], off offset:1024
	global_load_dwordx4 v[38:41], v[8:9], off offset:2048
	global_load_dwordx4 v[42:45], v[6:7], off offset:1024
	global_load_dwordx4 v[46:49], v[6:7], off offset:2048
	v_sub_u32_e32 v3, 63, v14
	v_cvt_f32_i32_e32 v3, v3
	v_mul_u32_u24_e32 v6, 0x140, v12
	v_sub_u32_e32 v7, 31, v14
	v_lshl_or_b32 v8, v13, 1, v6
	v_mul_f32_e32 v6, v5, v3
	v_cvt_f32_i32_e32 v7, v7
	v_cmp_gt_f32_e32 vcc, s51, v6
	s_ashr_i32 s10, s8, 7
	s_lshr_b32 s0, s8, 5
	v_cndmask_b32_e32 v6, 0, v187, vcc
	v_fmac_f32_e32 v6, v5, v3
	v_exp_f32_e32 v3, v6
	v_mul_f32_e32 v6, v5, v7
	v_cmp_gt_f32_e64 s[8:9], s51, v6
	v_lshlrev_b32_e32 v4, 6, v178
	s_and_b32 s4, s0, 2
	v_cndmask_b32_e64 v6, 0, v187, s[8:9]
	v_fmac_f32_e32 v6, v5, v7
	v_exp_f32_e32 v5, v6
	v_cndmask_b32_e32 v6, 0, v188, vcc
	v_ldexp_f32 v52, v3, v6
	v_cndmask_b32_e64 v3, 0, v188, s[8:9]
	v_lshl_add_u64 v[6:7], s[18:19], 0, v[0:1]
	s_lshl_b32 s5, s10, 12
	s_lshl_b32 s11, s4, 5
	v_ldexp_f32 v54, v5, v3
	v_lshl_add_u64 v[56:57], v[6:7], 0, v[10:11]
	v_ashrrev_i32_e32 v5, 31, v4
	v_lshl_or_b32 v6, v62, 9, s5
	v_lshlrev_b64 v[4:5], 15, v[4:5]
	v_or3_b32 v6, v6, s11, v63
	v_ashrrev_i32_e32 v7, 31, v6
	v_lshl_add_u64 v[4:5], s[14:15], 0, v[4:5]
	v_lshl_add_u64 v[58:59], v[6:7], 1, v[4:5]
	v_or_b32_e32 v6, 32, v6
	v_mov_b32_e32 v2, 0
	s_or_b32 s0, s4, 1
	v_add_u32_e32 v3, 0, v10
	v_add_u32_e32 v0, 0, v8
	v_mul_lo_u32 v8, v14, s53
	v_ashrrev_i32_e32 v7, 31, v6
	s_mov_b32 s1, 0
	s_lshl_b32 s8, s10, 6
	s_lshl_b32 s9, s4, 6
	s_lshl_b32 s24, s0, 6
	v_mov_b32_e32 v51, v50
	v_mov_b32_e32 v53, v52
	v_mov_b32_e32 v55, v54
	v_lshl_add_u64 v[60:61], v[6:7], 1, v[4:5]
	v_add_u32_e32 v64, 0x60, v15
	s_mov_b64 s[4:5], 0
	v_add_u32_e32 v65, v3, v8
	v_mov_b32_e32 v3, v2
	v_mov_b32_e32 v4, v2
	v_mov_b32_e32 v5, v2
	v_mov_b32_e32 v6, v2
	v_mov_b32_e32 v7, v2
	v_mov_b32_e32 v8, v2
	v_mov_b32_e32 v9, v2
	v_mov_b32_e32 v10, v2
	v_mov_b32_e32 v11, v2
	v_mov_b32_e32 v12, v2
	v_mov_b32_e32 v13, v2
	v_mov_b32_e32 v14, v2
	v_mov_b32_e32 v15, v2
	v_mov_b32_e32 v16, v2
	v_mov_b32_e32 v17, v2
	v_mov_b32_e32 v18, v2
	v_mov_b32_e32 v19, v2
	v_mov_b32_e32 v20, v2
	v_mov_b32_e32 v21, v2
	v_mov_b32_e32 v22, v2
	v_mov_b32_e32 v23, v2
	v_mov_b32_e32 v24, v2
	v_mov_b32_e32 v25, v2
	v_mov_b32_e32 v26, v2
	v_mov_b32_e32 v27, v2
	v_mov_b32_e32 v28, v2
	v_mov_b32_e32 v29, v2
	v_mov_b32_e32 v30, v2
	v_mov_b32_e32 v31, v2
	v_mov_b32_e32 v32, v2
	v_mov_b32_e32 v33, v2
	s_waitcnt vmcnt(0)
	s_branch .LBB0_751

.LBB0_751:
	s_waitcnt vmcnt(35)
	v_lshlrev_b32_e32 v66, 16, v34
	v_and_b32_e32 v67, 0xffff0000, v34
	v_lshlrev_b32_e32 v68, 16, v35
	v_and_b32_e32 v69, 0xffff0000, v35
	v_pk_mul_f32 v[66:67], v[52:53], v[66:67]
	v_pk_mul_f32 v[68:69], v[52:53], v[68:69]
	v_cvt_pk_bf16_f32 v66, v66, v67
	v_cvt_pk_bf16_f32 v67, v68, v69
	v_lshlrev_b32_e32 v68, 16, v36
	v_and_b32_e32 v69, 0xffff0000, v36
	v_lshlrev_b32_e32 v70, 16, v37
	v_and_b32_e32 v71, 0xffff0000, v37
	v_pk_mul_f32 v[68:69], v[52:53], v[68:69]
	v_pk_mul_f32 v[70:71], v[52:53], v[70:71]
	v_cvt_pk_bf16_f32 v68, v68, v69
	v_cvt_pk_bf16_f32 v69, v70, v71
	ds_write_b128 v65, v[66:69]
	s_waitcnt vmcnt(34)
	ds_write_b128 v65, v[38:41] offset:20480
	s_waitcnt vmcnt(33)
	v_lshlrev_b32_e32 v66, 16, v42
	v_and_b32_e32 v67, 0xffff0000, v42
	v_lshlrev_b32_e32 v68, 16, v43
	v_and_b32_e32 v69, 0xffff0000, v43
	v_pk_mul_f32 v[66:67], v[54:55], v[66:67]
	v_pk_mul_f32 v[68:69], v[54:55], v[68:69]
	v_cvt_pk_bf16_f32 v66, v66, v67
	v_cvt_pk_bf16_f32 v67, v68, v69
	v_lshlrev_b32_e32 v68, 16, v44
	v_and_b32_e32 v69, 0xffff0000, v44
	v_lshlrev_b32_e32 v70, 16, v45
	v_and_b32_e32 v71, 0xffff0000, v45
	v_pk_mul_f32 v[68:69], v[54:55], v[68:69]
	v_pk_mul_f32 v[70:71], v[54:55], v[70:71]
	v_cvt_pk_bf16_f32 v68, v68, v69
	v_cvt_pk_bf16_f32 v69, v70, v71
	s_cmp_gt_u32 s1, 62
	ds_write_b128 v65, v[66:69] offset:10240
	s_waitcnt vmcnt(32)
	ds_write_b128 v65, v[46:49] offset:30720
	s_waitcnt lgkmcnt(0)
	s_barrier
	s_cbranch_scc1 .LBB0_750
	v_subrev_u32_e32 v34, 32, v64
	v_mad_i64_i32 v[38:39], s[26:27], v34, s52, v[56:57]
	v_mad_i64_i32 v[46:47], s[26:27], v64, s52, v[56:57]
	global_load_dwordx4 v[34:37], v[38:39], off offset:1024
	s_nop 0
	global_load_dwordx4 v[38:41], v[38:39], off offset:2048
	s_nop 0
	global_load_dwordx4 v[42:45], v[46:47], off offset:1024
	s_nop 0
	global_load_dwordx4 v[46:49], v[46:47], off offset:2048
	s_branch .LBB0_750

.LBB0_1155:
	v_mul_f32_e32 v155, 0xbfb8aa3b, v124
	v_exp_f32_e32 v155, v155
	v_mul_f32_e32 v158, 0xbfb8aa3b, v125
	v_exp_f32_e32 v159, v158
	v_lshl_add_u32 v154, s22, 8, v148
	v_add_f32_e32 v155, 1.0, v155
	v_rcp_f32_e32 v158, v155
	v_add_f32_e32 v155, 1.0, v159
	v_mul_f32_e32 v159, 0xbfb8aa3b, v126
	v_exp_f32_e32 v160, v159
	v_mul_f32_e32 v159, 0xbfb8aa3b, v127
	v_exp_f32_e32 v161, v159
	v_rcp_f32_e32 v159, v155
	v_add_f32_e32 v155, 1.0, v160
	v_rcp_f32_e32 v160, v155
	v_add_f32_e32 v155, 1.0, v161
	v_rcp_f32_e32 v161, v155
	v_pk_mul_f32 v[124:125], v[124:125], v[158:159]
	v_lshl_or_b32 v144, s43, 7, v150
	v_pk_mul_f32 v[120:121], v[124:125], v[120:121]
	v_pk_mul_f32 v[124:125], v[126:127], v[160:161]
	v_cvt_pk_bf16_f32 v120, v120, v121
	v_mul_f32_e32 v121, 0xbfb8aa3b, v116
	v_pk_mul_f32 v[122:123], v[124:125], v[122:123]
	v_exp_f32_e32 v124, v121
	v_mul_f32_e32 v121, 0xbfb8aa3b, v117
	v_exp_f32_e32 v125, v121
	v_cvt_pk_bf16_f32 v121, v122, v123
	v_add_f32_e32 v122, 1.0, v124
	v_mul_f32_e32 v124, 0xbfb8aa3b, v118
	v_add_f32_e32 v123, 1.0, v125
	v_mul_f32_e32 v125, 0xbfb8aa3b, v119
	v_exp_f32_e32 v124, v124
	v_exp_f32_e32 v125, v125
	v_rcp_f32_e32 v122, v122
	v_rcp_f32_e32 v123, v123
	v_add_f32_e32 v124, 1.0, v124
	v_add_f32_e32 v125, 1.0, v125
	v_rcp_f32_e32 v124, v124
	v_rcp_f32_e32 v125, v125
	v_pk_mul_f32 v[116:117], v[116:117], v[122:123]
	v_ashrrev_i32_e32 v145, 31, v144
	v_pk_mul_f32 v[112:113], v[116:117], v[112:113]
	v_mul_f32_e32 v116, 0xbfb8aa3b, v110
	v_cvt_pk_bf16_f32 v122, v112, v113
	v_pk_mul_f32 v[112:113], v[118:119], v[124:125]
	v_mul_f32_e32 v117, 0xbfb8aa3b, v111
	v_pk_mul_f32 v[112:113], v[112:113], v[114:115]
	v_mul_f32_e32 v114, 0xbfb8aa3b, v108
	v_mul_f32_e32 v115, 0xbfb8aa3b, v109
	v_exp_f32_e32 v114, v114
	v_exp_f32_e32 v115, v115
	v_exp_f32_e32 v116, v116
	v_exp_f32_e32 v117, v117
	v_add_f32_e32 v114, 1.0, v114
	v_add_f32_e32 v115, 1.0, v115
	v_rcp_f32_e32 v114, v114
	v_rcp_f32_e32 v115, v115
	v_add_f32_e32 v116, 1.0, v116
	v_add_f32_e32 v117, 1.0, v117
	v_rcp_f32_e32 v116, v116
	v_rcp_f32_e32 v117, v117
	v_pk_mul_f32 v[108:109], v[108:109], v[114:115]
	v_mov_b64_e32 v[146:147], s[8:9]
	v_pk_mul_f32 v[104:105], v[108:109], v[104:105]
	v_pk_mul_f32 v[108:109], v[110:111], v[116:117]
	v_cvt_pk_bf16_f32 v104, v104, v105
	v_mul_f32_e32 v105, 0xbfb8aa3b, v100
	v_pk_mul_f32 v[106:107], v[108:109], v[106:107]
	v_exp_f32_e32 v108, v105
	v_mul_f32_e32 v105, 0xbfb8aa3b, v101
	v_exp_f32_e32 v109, v105
	v_cvt_pk_bf16_f32 v105, v106, v107
	v_add_f32_e32 v106, 1.0, v108
	v_mul_f32_e32 v108, 0xbfb8aa3b, v102
	v_add_f32_e32 v107, 1.0, v109
	v_mul_f32_e32 v109, 0xbfb8aa3b, v103
	v_exp_f32_e32 v108, v108
	v_exp_f32_e32 v109, v109
	v_rcp_f32_e32 v106, v106
	v_rcp_f32_e32 v107, v107
	v_add_f32_e32 v108, 1.0, v108
	v_add_f32_e32 v109, 1.0, v109
	v_rcp_f32_e32 v108, v108
	v_rcp_f32_e32 v109, v109
	v_pk_mul_f32 v[100:101], v[100:101], v[106:107]
	v_cvt_pk_bf16_f32 v123, v112, v113
	v_pk_mul_f32 v[96:97], v[100:101], v[96:97]
	v_mul_f32_e32 v100, 0xbfb8aa3b, v94
	v_cvt_pk_bf16_f32 v106, v96, v97
	v_pk_mul_f32 v[96:97], v[102:103], v[108:109]
	v_mul_f32_e32 v101, 0xbfb8aa3b, v95
	v_pk_mul_f32 v[96:97], v[96:97], v[98:99]
	v_mul_f32_e32 v98, 0xbfb8aa3b, v92
	v_mul_f32_e32 v99, 0xbfb8aa3b, v93
	v_exp_f32_e32 v98, v98
	v_exp_f32_e32 v99, v99
	v_exp_f32_e32 v100, v100
	v_exp_f32_e32 v101, v101
	v_add_f32_e32 v98, 1.0, v98
	v_add_f32_e32 v99, 1.0, v99
	v_rcp_f32_e32 v98, v98
	v_rcp_f32_e32 v99, v99
	v_add_f32_e32 v100, 1.0, v100
	v_add_f32_e32 v101, 1.0, v101
	v_rcp_f32_e32 v100, v100
	v_rcp_f32_e32 v101, v101
	v_pk_mul_f32 v[92:93], v[92:93], v[98:99]
	v_or_b32_e32 v112, 16, v154
	v_pk_mul_f32 v[88:89], v[92:93], v[88:89]
	v_pk_mul_f32 v[92:93], v[94:95], v[100:101]
	v_cvt_pk_bf16_f32 v88, v88, v89
	v_mul_f32_e32 v89, 0xbfb8aa3b, v84
	v_pk_mul_f32 v[90:91], v[92:93], v[90:91]
	v_exp_f32_e32 v92, v89
	v_mul_f32_e32 v89, 0xbfb8aa3b, v85
	v_exp_f32_e32 v93, v89
	v_cvt_pk_bf16_f32 v89, v90, v91
	v_add_f32_e32 v90, 1.0, v92
	v_mul_f32_e32 v92, 0xbfb8aa3b, v86
	v_add_f32_e32 v91, 1.0, v93
	v_mul_f32_e32 v93, 0xbfb8aa3b, v87
	v_exp_f32_e32 v92, v92
	v_exp_f32_e32 v93, v93
	v_rcp_f32_e32 v90, v90
	v_rcp_f32_e32 v91, v91
	v_add_f32_e32 v92, 1.0, v92
	v_add_f32_e32 v93, 1.0, v93
	v_rcp_f32_e32 v92, v92
	v_rcp_f32_e32 v93, v93
	v_pk_mul_f32 v[84:85], v[84:85], v[90:91]
	v_cvt_pk_bf16_f32 v107, v96, v97
	v_pk_mul_f32 v[80:81], v[84:85], v[80:81]
	v_mul_f32_e32 v84, 0xbfb8aa3b, v78
	v_cvt_pk_bf16_f32 v90, v80, v81
	v_pk_mul_f32 v[80:81], v[86:87], v[92:93]
	v_mul_f32_e32 v85, 0xbfb8aa3b, v79
	v_pk_mul_f32 v[80:81], v[80:81], v[82:83]
	v_mul_f32_e32 v82, 0xbfb8aa3b, v76
	v_mul_f32_e32 v83, 0xbfb8aa3b, v77
	v_exp_f32_e32 v82, v82
	v_exp_f32_e32 v83, v83
	v_exp_f32_e32 v84, v84
	v_exp_f32_e32 v85, v85
	v_add_f32_e32 v82, 1.0, v82
	v_add_f32_e32 v83, 1.0, v83
	v_rcp_f32_e32 v82, v82
	v_rcp_f32_e32 v83, v83
	v_add_f32_e32 v84, 1.0, v84
	v_add_f32_e32 v85, 1.0, v85
	v_rcp_f32_e32 v84, v84
	v_rcp_f32_e32 v85, v85
	v_pk_mul_f32 v[76:77], v[76:77], v[82:83]
	v_or_b32_e32 v96, 32, v154
	v_pk_mul_f32 v[72:73], v[76:77], v[72:73]
	v_pk_mul_f32 v[76:77], v[78:79], v[84:85]
	v_cvt_pk_bf16_f32 v72, v72, v73
	v_mul_f32_e32 v73, 0xbfb8aa3b, v68
	v_pk_mul_f32 v[74:75], v[76:77], v[74:75]
	v_exp_f32_e32 v76, v73
	v_mul_f32_e32 v73, 0xbfb8aa3b, v69
	v_exp_f32_e32 v77, v73
	v_cvt_pk_bf16_f32 v73, v74, v75
	v_add_f32_e32 v74, 1.0, v76
	v_mul_f32_e32 v76, 0xbfb8aa3b, v70
	v_add_f32_e32 v75, 1.0, v77
	v_mul_f32_e32 v77, 0xbfb8aa3b, v71
	v_exp_f32_e32 v76, v76
	v_exp_f32_e32 v77, v77
	v_rcp_f32_e32 v74, v74
	v_rcp_f32_e32 v75, v75
	v_add_f32_e32 v76, 1.0, v76
	v_add_f32_e32 v77, 1.0, v77
	v_rcp_f32_e32 v76, v76
	v_rcp_f32_e32 v77, v77
	v_pk_mul_f32 v[68:69], v[68:69], v[74:75]
	v_cvt_pk_bf16_f32 v91, v80, v81
	v_pk_mul_f32 v[64:65], v[68:69], v[64:65]
	v_mul_f32_e32 v68, 0xbfb8aa3b, v62
	v_cvt_pk_bf16_f32 v74, v64, v65
	v_pk_mul_f32 v[64:65], v[70:71], v[76:77]
	v_mul_f32_e32 v69, 0xbfb8aa3b, v63
	v_pk_mul_f32 v[64:65], v[64:65], v[66:67]
	v_mul_f32_e32 v66, 0xbfb8aa3b, v60
	v_mul_f32_e32 v67, 0xbfb8aa3b, v61
	v_exp_f32_e32 v66, v66
	v_exp_f32_e32 v67, v67
	v_exp_f32_e32 v68, v68
	v_exp_f32_e32 v69, v69
	v_add_f32_e32 v66, 1.0, v66
	v_add_f32_e32 v67, 1.0, v67
	v_rcp_f32_e32 v66, v66
	v_rcp_f32_e32 v67, v67
	v_add_f32_e32 v68, 1.0, v68
	v_add_f32_e32 v69, 1.0, v69
	v_rcp_f32_e32 v68, v68
	v_rcp_f32_e32 v69, v69
	v_pk_mul_f32 v[60:61], v[60:61], v[66:67]
	v_or_b32_e32 v80, 48, v154
	v_pk_mul_f32 v[56:57], v[60:61], v[56:57]
	v_pk_mul_f32 v[60:61], v[62:63], v[68:69]
	v_cvt_pk_bf16_f32 v56, v56, v57
	v_mul_f32_e32 v57, 0xbfb8aa3b, v52
	v_pk_mul_f32 v[58:59], v[60:61], v[58:59]
	v_exp_f32_e32 v60, v57
	v_mul_f32_e32 v57, 0xbfb8aa3b, v53
	v_exp_f32_e32 v61, v57
	v_cvt_pk_bf16_f32 v57, v58, v59
	v_add_f32_e32 v58, 1.0, v60
	v_mul_f32_e32 v60, 0xbfb8aa3b, v54
	v_add_f32_e32 v59, 1.0, v61
	v_mul_f32_e32 v61, 0xbfb8aa3b, v55
	v_exp_f32_e32 v60, v60
	v_exp_f32_e32 v61, v61
	v_rcp_f32_e32 v58, v58
	v_rcp_f32_e32 v59, v59
	v_add_f32_e32 v60, 1.0, v60
	v_add_f32_e32 v61, 1.0, v61
	v_rcp_f32_e32 v60, v60
	v_rcp_f32_e32 v61, v61
	v_pk_mul_f32 v[52:53], v[52:53], v[58:59]
	v_cvt_pk_bf16_f32 v75, v64, v65
	v_pk_mul_f32 v[48:49], v[52:53], v[48:49]
	v_mul_f32_e32 v52, 0xbfb8aa3b, v46
	v_cvt_pk_bf16_f32 v58, v48, v49
	v_pk_mul_f32 v[48:49], v[54:55], v[60:61]
	v_mul_f32_e32 v53, 0xbfb8aa3b, v47
	v_pk_mul_f32 v[48:49], v[48:49], v[50:51]
	v_mul_f32_e32 v50, 0xbfb8aa3b, v44
	v_mul_f32_e32 v51, 0xbfb8aa3b, v45
	v_exp_f32_e32 v50, v50
	v_exp_f32_e32 v51, v51
	v_exp_f32_e32 v52, v52
	v_exp_f32_e32 v53, v53
	v_add_f32_e32 v50, 1.0, v50
	v_add_f32_e32 v51, 1.0, v51
	v_rcp_f32_e32 v50, v50
	v_rcp_f32_e32 v51, v51
	v_add_f32_e32 v52, 1.0, v52
	v_add_f32_e32 v53, 1.0, v53
	v_rcp_f32_e32 v52, v52
	v_rcp_f32_e32 v53, v53
	v_pk_mul_f32 v[44:45], v[44:45], v[50:51]
	v_add_u32_e32 v64, 0x80, v154
	v_pk_mul_f32 v[40:41], v[44:45], v[40:41]
	v_pk_mul_f32 v[44:45], v[46:47], v[52:53]
	v_cvt_pk_bf16_f32 v40, v40, v41
	v_mul_f32_e32 v41, 0xbfb8aa3b, v36
	v_pk_mul_f32 v[42:43], v[44:45], v[42:43]
	v_exp_f32_e32 v44, v41
	v_mul_f32_e32 v41, 0xbfb8aa3b, v37
	v_exp_f32_e32 v45, v41
	v_cvt_pk_bf16_f32 v41, v42, v43
	v_add_f32_e32 v42, 1.0, v44
	v_mul_f32_e32 v44, 0xbfb8aa3b, v38
	v_add_f32_e32 v43, 1.0, v45
	v_mul_f32_e32 v45, 0xbfb8aa3b, v39
	v_exp_f32_e32 v44, v44
	v_exp_f32_e32 v45, v45
	v_rcp_f32_e32 v42, v42
	v_rcp_f32_e32 v43, v43
	v_add_f32_e32 v44, 1.0, v44
	v_add_f32_e32 v45, 1.0, v45
	v_rcp_f32_e32 v44, v44
	v_rcp_f32_e32 v45, v45
	v_pk_mul_f32 v[36:37], v[36:37], v[42:43]
	v_cvt_pk_bf16_f32 v59, v48, v49
	v_pk_mul_f32 v[32:33], v[36:37], v[32:33]
	v_mul_f32_e32 v36, 0xbfb8aa3b, v30
	v_cvt_pk_bf16_f32 v42, v32, v33
	v_pk_mul_f32 v[32:33], v[38:39], v[44:45]
	v_mul_f32_e32 v37, 0xbfb8aa3b, v31
	v_pk_mul_f32 v[32:33], v[32:33], v[34:35]
	v_mul_f32_e32 v34, 0xbfb8aa3b, v28
	v_mul_f32_e32 v35, 0xbfb8aa3b, v29
	v_exp_f32_e32 v34, v34
	v_exp_f32_e32 v35, v35
	v_exp_f32_e32 v36, v36
	v_exp_f32_e32 v37, v37
	v_add_f32_e32 v34, 1.0, v34
	v_add_f32_e32 v35, 1.0, v35
	v_rcp_f32_e32 v34, v34
	v_rcp_f32_e32 v35, v35
	v_add_f32_e32 v36, 1.0, v36
	v_add_f32_e32 v37, 1.0, v37
	v_rcp_f32_e32 v36, v36
	v_rcp_f32_e32 v37, v37
	v_pk_mul_f32 v[28:29], v[28:29], v[34:35]
	v_add_u32_e32 v48, 0x90, v154
	v_pk_mul_f32 v[24:25], v[28:29], v[24:25]
	v_pk_mul_f32 v[28:29], v[30:31], v[36:37]
	v_cvt_pk_bf16_f32 v24, v24, v25
	v_mul_f32_e32 v25, 0xbfb8aa3b, v20
	v_pk_mul_f32 v[26:27], v[28:29], v[26:27]
	v_exp_f32_e32 v28, v25
	v_mul_f32_e32 v25, 0xbfb8aa3b, v21
	v_exp_f32_e32 v29, v25
	v_cvt_pk_bf16_f32 v25, v26, v27
	v_add_f32_e32 v26, 1.0, v28
	v_mul_f32_e32 v28, 0xbfb8aa3b, v22
	v_add_f32_e32 v27, 1.0, v29
	v_mul_f32_e32 v29, 0xbfb8aa3b, v23
	v_exp_f32_e32 v28, v28
	v_exp_f32_e32 v29, v29
	v_rcp_f32_e32 v26, v26
	v_rcp_f32_e32 v27, v27
	v_add_f32_e32 v28, 1.0, v28
	v_add_f32_e32 v29, 1.0, v29
	v_rcp_f32_e32 v28, v28
	v_rcp_f32_e32 v29, v29
	v_pk_mul_f32 v[20:21], v[20:21], v[26:27]
	v_cvt_pk_bf16_f32 v43, v32, v33
	v_pk_mul_f32 v[16:17], v[20:21], v[16:17]
	v_mul_f32_e32 v20, 0xbfb8aa3b, v14
	v_cvt_pk_bf16_f32 v26, v16, v17
	v_pk_mul_f32 v[16:17], v[22:23], v[28:29]
	v_mul_f32_e32 v21, 0xbfb8aa3b, v15
	v_pk_mul_f32 v[16:17], v[16:17], v[18:19]
	v_mul_f32_e32 v18, 0xbfb8aa3b, v12
	v_mul_f32_e32 v19, 0xbfb8aa3b, v13
	v_exp_f32_e32 v18, v18
	v_exp_f32_e32 v19, v19
	v_exp_f32_e32 v20, v20
	v_exp_f32_e32 v21, v21
	v_add_f32_e32 v18, 1.0, v18
	v_add_f32_e32 v19, 1.0, v19
	v_rcp_f32_e32 v18, v18
	v_rcp_f32_e32 v19, v19
	v_add_f32_e32 v20, 1.0, v20
	v_add_f32_e32 v21, 1.0, v21
	v_rcp_f32_e32 v20, v20
	v_rcp_f32_e32 v21, v21
	v_pk_mul_f32 v[12:13], v[12:13], v[18:19]
	v_add_u32_e32 v32, 0xa0, v154
	v_pk_mul_f32 v[8:9], v[12:13], v[8:9]
	v_pk_mul_f32 v[12:13], v[14:15], v[20:21]
	v_cvt_pk_bf16_f32 v8, v8, v9
	v_mul_f32_e32 v9, 0xbfb8aa3b, v4
	v_pk_mul_f32 v[10:11], v[12:13], v[10:11]
	v_exp_f32_e32 v12, v9
	v_mul_f32_e32 v9, 0xbfb8aa3b, v5
	v_exp_f32_e32 v13, v9
	v_cvt_pk_bf16_f32 v9, v10, v11
	v_add_f32_e32 v10, 1.0, v12
	v_mul_f32_e32 v12, 0xbfb8aa3b, v6
	v_add_f32_e32 v11, 1.0, v13
	v_mul_f32_e32 v13, 0xbfb8aa3b, v7
	v_exp_f32_e32 v12, v12
	v_exp_f32_e32 v13, v13
	v_rcp_f32_e32 v10, v10
	v_rcp_f32_e32 v11, v11
	v_add_f32_e32 v12, 1.0, v12
	v_add_f32_e32 v13, 1.0, v13
	v_rcp_f32_e32 v12, v12
	v_rcp_f32_e32 v13, v13
	v_pk_mul_f32 v[4:5], v[4:5], v[10:11]
	v_cvt_pk_bf16_f32 v27, v16, v17
	v_pk_mul_f32 v[0:1], v[4:5], v[0:1]
	v_add_u32_e32 v16, 0xb0, v154
	v_cvt_pk_bf16_f32 v10, v0, v1
	v_pk_mul_f32 v[0:1], v[6:7], v[12:13]
	v_mad_i64_i32 v[156:157], s[24:25], v154, s42, v[146:147]
	v_lshlrev_b64 v[144:145], 1, v[144:145]
	v_mad_i64_i32 v[112:113], s[24:25], v112, s42, v[146:147]
	v_mad_i64_i32 v[96:97], s[24:25], v96, s42, v[146:147]
	v_mad_i64_i32 v[80:81], s[24:25], v80, s42, v[146:147]
	v_mad_i64_i32 v[64:65], s[24:25], v64, s42, v[146:147]
	v_mad_i64_i32 v[48:49], s[24:25], v48, s42, v[146:147]
	v_mad_i64_i32 v[32:33], s[24:25], v32, s42, v[146:147]
	v_mad_i64_i32 v[16:17], s[24:25], v16, s42, v[146:147]
	v_pk_mul_f32 v[0:1], v[0:1], v[2:3]
	v_lshl_add_u64 v[156:157], v[156:157], 0, v[144:145]
	v_lshl_add_u64 v[112:113], v[112:113], 0, v[144:145]
	v_lshl_add_u64 v[96:97], v[96:97], 0, v[144:145]
	v_lshl_add_u64 v[80:81], v[80:81], 0, v[144:145]
	v_lshl_add_u64 v[64:65], v[64:65], 0, v[144:145]
	v_lshl_add_u64 v[48:49], v[48:49], 0, v[144:145]
	v_lshl_add_u64 v[32:33], v[32:33], 0, v[144:145]
	v_lshl_add_u64 v[16:17], v[16:17], 0, v[144:145]
	v_cvt_pk_bf16_f32 v11, v0, v1
	s_andn2_b64 vcc, exec, s[6:7]
	s_mov_b64 s[6:7], -1
	v_and_b32_e32 v226, 63, v252
	v_lshlrev_b32_e32 v227, 4, v226
	v_and_b32_e32 v227, 0x30, v227
	v_lshrrev_b32_e32 v228, 4, v226
	v_and_or_b32 v227, v226, 12, v227
	v_or_b32_e32 v227, v227, v228
	v_lshlrev_b32_e32 v226, 2, v227
	ds_bpermute_b32 v230, v226, v120
	ds_bpermute_b32 v231, v226, v121
	ds_bpermute_b32 v232, v226, v122
	ds_bpermute_b32 v233, v226, v123
	ds_bpermute_b32 v234, v226, v156
	ds_bpermute_b32 v235, v226, v157
	ds_bpermute_b32 v236, v226, v104
	ds_bpermute_b32 v237, v226, v105
	ds_bpermute_b32 v238, v226, v106
	ds_bpermute_b32 v239, v226, v107
	ds_bpermute_b32 v240, v226, v112
	ds_bpermute_b32 v241, v226, v113
	s_waitcnt lgkmcnt(6)
	global_store_dwordx4 v[234:235], v[230:233], off
	s_nop 0
	ds_bpermute_b32 v230, v226, v88
	ds_bpermute_b32 v231, v226, v89
	ds_bpermute_b32 v232, v226, v90
	ds_bpermute_b32 v233, v226, v91
	ds_bpermute_b32 v234, v226, v96
	ds_bpermute_b32 v235, v226, v97
	s_waitcnt lgkmcnt(6)
	global_store_dwordx4 v[240:241], v[236:239], off
	s_nop 0
	ds_bpermute_b32 v236, v226, v72
	ds_bpermute_b32 v237, v226, v73
	ds_bpermute_b32 v238, v226, v74
	ds_bpermute_b32 v239, v226, v75
	ds_bpermute_b32 v240, v226, v80
	ds_bpermute_b32 v241, v226, v81
	s_waitcnt lgkmcnt(6)
	global_store_dwordx4 v[234:235], v[230:233], off
	s_nop 0
	ds_bpermute_b32 v230, v226, v56
	ds_bpermute_b32 v231, v226, v57
	ds_bpermute_b32 v232, v226, v58
	ds_bpermute_b32 v233, v226, v59
	ds_bpermute_b32 v234, v226, v64
	ds_bpermute_b32 v235, v226, v65
	s_waitcnt lgkmcnt(6)
	global_store_dwordx4 v[240:241], v[236:239], off
	s_nop 0
	ds_bpermute_b32 v236, v226, v40
	ds_bpermute_b32 v237, v226, v41
	ds_bpermute_b32 v238, v226, v42
	ds_bpermute_b32 v239, v226, v43
	ds_bpermute_b32 v240, v226, v48
	ds_bpermute_b32 v241, v226, v49
	s_waitcnt lgkmcnt(6)
	global_store_dwordx4 v[234:235], v[230:233], off
	s_nop 0
	ds_bpermute_b32 v230, v226, v24
	ds_bpermute_b32 v231, v226, v25
	ds_bpermute_b32 v232, v226, v26
	ds_bpermute_b32 v233, v226, v27
	ds_bpermute_b32 v234, v226, v32
	ds_bpermute_b32 v235, v226, v33
	s_waitcnt lgkmcnt(6)
	global_store_dwordx4 v[240:241], v[236:239], off
	s_nop 0
	ds_bpermute_b32 v236, v226, v8
	ds_bpermute_b32 v237, v226, v9
	ds_bpermute_b32 v238, v226, v10
	ds_bpermute_b32 v239, v226, v11
	ds_bpermute_b32 v240, v226, v16
	ds_bpermute_b32 v241, v226, v17
	s_waitcnt lgkmcnt(6)
	global_store_dwordx4 v[234:235], v[230:233], off
	s_nop 0
	s_waitcnt lgkmcnt(0)
	global_store_dwordx4 v[240:241], v[236:239], off
	s_nop 0
	s_cbranch_vccnz .LBB0_1144
	s_andn2_b64 vcc, exec, s[4:5]
	s_cbranch_vccnz .LBB0_1143
	s_barrier
	s_branch .LBB0_1143
